# RW1: redundant lgkmcnt(0) at the GEMM K-loop head removed, on top of v082
# speedup vs baseline: 1.0007x; 1.0007x over previous
.LBB0_169:
	s_add_i32 s0, s34, 2
	s_add_u32 s1, s80, 0x80
	s_addc_u32 s35, s81, 0
	s_add_i32 s47, 0, 0x10000
	s_cmp_eq_u32 s68, s34
	s_cselect_b32 s35, s43, s35
	s_cselect_b32 s34, s42, s1
	s_cselect_b32 s67, s87, vcc_hi
	s_cselect_b32 s66, s86, vcc_lo
	s_add_i32 s1, 0, 0x14000
	ds_read_b128 v[130:133], v206
	ds_read_b128 v[134:137], v206 offset:1024
	ds_read_b128 v[138:141], v206 offset:2048
	ds_read_b128 v[142:145], v206 offset:3072
	ds_read_b128 v[146:149], v207
	ds_read_b128 v[150:153], v207 offset:1024
	ds_read_b128 v[154:157], v207 offset:2048
	ds_read_b128 v[158:161], v207 offset:3072
	s_add_i32 m0, s90, 0xc000
	ds_read_b128 v[162:165], v238
	ds_read_b128 v[166:169], v238 offset:1024
	ds_read_b128 v[170:173], v238 offset:2048
	ds_read_b128 v[174:177], v238 offset:3072
	ds_read_b128 v[178:181], v238 offset:4096
	ds_read_b128 v[182:185], v238 offset:5120
	ds_read_b128 v[198:201], v238 offset:6144
	ds_read_b128 v[202:205], v238 offset:7168
	global_load_lds_dwordx4 v194, s[80:81]
	s_add_i32 m0, s90, 0xe000
	s_nop 0
	global_load_lds_dwordx4 v196, s[80:81]
	s_waitcnt vmcnt(8)
	s_waitcnt lgkmcnt(0)
	s_barrier
	v_mfma_f32_16x16x32_bf16 v[126:129], v[130:133], v[162:165], v[126:129]
	v_mfma_f32_16x16x32_bf16 v[122:125], v[138:141], v[162:165], v[122:125]
	v_mfma_f32_16x16x32_bf16 v[118:121], v[130:133], v[170:173], v[118:121]
	v_mfma_f32_16x16x32_bf16 v[102:105], v[138:141], v[170:173], v[102:105]
	v_mfma_f32_16x16x32_bf16 v[94:97], v[130:133], v[178:181], v[94:97]
	v_mfma_f32_16x16x32_bf16 v[90:93], v[138:141], v[178:181], v[90:93]
	v_mfma_f32_16x16x32_bf16 v[78:81], v[130:133], v[198:201], v[78:81]
	v_mfma_f32_16x16x32_bf16 v[74:77], v[138:141], v[198:201], v[74:77]
	v_mfma_f32_16x16x32_bf16 v[126:129], v[134:137], v[166:169], v[126:129]
	v_mfma_f32_16x16x32_bf16 v[122:125], v[142:145], v[166:169], v[122:125]
	v_mfma_f32_16x16x32_bf16 v[118:121], v[134:137], v[174:177], v[118:121]
	v_mfma_f32_16x16x32_bf16 v[102:105], v[142:145], v[174:177], v[102:105]
	v_mfma_f32_16x16x32_bf16 v[94:97], v[134:137], v[182:185], v[94:97]
	v_mfma_f32_16x16x32_bf16 v[90:93], v[142:145], v[182:185], v[90:93]
	v_mfma_f32_16x16x32_bf16 v[78:81], v[134:137], v[202:205], v[78:81]
	v_mfma_f32_16x16x32_bf16 v[74:77], v[142:145], v[202:205], v[74:77]
	v_mfma_f32_16x16x32_bf16 v[114:117], v[146:149], v[162:165], v[114:117]
	v_mfma_f32_16x16x32_bf16 v[110:113], v[154:157], v[162:165], v[110:113]
	v_mfma_f32_16x16x32_bf16 v[106:109], v[146:149], v[170:173], v[106:109]
	v_mfma_f32_16x16x32_bf16 v[98:101], v[154:157], v[170:173], v[98:101]
	v_mfma_f32_16x16x32_bf16 v[86:89], v[146:149], v[178:181], v[86:89]
	v_mfma_f32_16x16x32_bf16 v[82:85], v[154:157], v[178:181], v[82:85]
	v_mfma_f32_16x16x32_bf16 v[70:73], v[146:149], v[198:201], v[70:73]
	v_mfma_f32_16x16x32_bf16 v[66:69], v[154:157], v[198:201], v[66:69]
	v_mfma_f32_16x16x32_bf16 v[114:117], v[150:153], v[166:169], v[114:117]
	v_mfma_f32_16x16x32_bf16 v[110:113], v[158:161], v[166:169], v[110:113]
	v_mfma_f32_16x16x32_bf16 v[106:109], v[150:153], v[174:177], v[106:109]
	v_mfma_f32_16x16x32_bf16 v[98:101], v[158:161], v[174:177], v[98:101]
	v_mfma_f32_16x16x32_bf16 v[86:89], v[150:153], v[182:185], v[86:89]
	v_mfma_f32_16x16x32_bf16 v[82:85], v[158:161], v[182:185], v[82:85]
	v_mfma_f32_16x16x32_bf16 v[70:73], v[150:153], v[202:205], v[70:73]
	v_mfma_f32_16x16x32_bf16 v[66:69], v[158:161], v[202:205], v[66:69]
	s_barrier
	s_add_i32 s47, s47, s57
	s_mov_b32 m0, s47
	ds_read_b128 v[162:165], v238 offset:16384
	ds_read_b128 v[166:169], v238 offset:17408
	ds_read_b128 v[170:173], v238 offset:18432
	ds_read_b128 v[174:177], v238 offset:19456
	ds_read_b128 v[178:181], v238 offset:20480
	ds_read_b128 v[182:185], v238 offset:21504
	ds_read_b128 v[198:201], v238 offset:22528
	ds_read_b128 v[202:205], v238 offset:23552
	global_load_lds_dwordx4 v188, s[66:67]
	s_add_i32 m0, s47, 0x2000
	s_add_u32 s100, s66, s69
	s_addc_u32 s101, s67, 0
	s_add_i32 s1, s1, s57
	global_load_lds_dwordx4 v192, s[66:67]
	s_mov_b32 m0, s1
	s_nop 0
	global_load_lds_dwordx4 v188, s[100:101]
	s_add_i32 m0, s1, 0x2000
	s_nop 0
	global_load_lds_dwordx4 v192, s[100:101]
	s_mov_b32 m0, s90
	s_nop 0
	global_load_lds_dwordx4 v186, s[34:35]
	s_mov_b32 m0, s60
	s_nop 0
	global_load_lds_dwordx4 v190, s[34:35]
	s_waitcnt vmcnt(8)
	s_waitcnt lgkmcnt(0)
	s_barrier
	v_mfma_f32_16x16x32_bf16 v[62:65], v[130:133], v[162:165], v[62:65]
	v_mfma_f32_16x16x32_bf16 v[58:61], v[138:141], v[162:165], v[58:61]
	v_mfma_f32_16x16x32_bf16 v[46:49], v[130:133], v[170:173], v[46:49]
	v_mfma_f32_16x16x32_bf16 v[42:45], v[138:141], v[170:173], v[42:45]
	v_mfma_f32_16x16x32_bf16 v[30:33], v[130:133], v[178:181], v[30:33]
	v_mfma_f32_16x16x32_bf16 v[26:29], v[138:141], v[178:181], v[26:29]
	v_mfma_f32_16x16x32_bf16 v[14:17], v[130:133], v[198:201], v[14:17]
	v_mfma_f32_16x16x32_bf16 v[10:13], v[138:141], v[198:201], v[10:13]
	v_mfma_f32_16x16x32_bf16 v[62:65], v[134:137], v[166:169], v[62:65]
	v_mfma_f32_16x16x32_bf16 v[58:61], v[142:145], v[166:169], v[58:61]
	v_mfma_f32_16x16x32_bf16 v[46:49], v[134:137], v[174:177], v[46:49]
	v_mfma_f32_16x16x32_bf16 v[42:45], v[142:145], v[174:177], v[42:45]
	v_mfma_f32_16x16x32_bf16 v[30:33], v[134:137], v[182:185], v[30:33]
	v_mfma_f32_16x16x32_bf16 v[26:29], v[142:145], v[182:185], v[26:29]
	v_mfma_f32_16x16x32_bf16 v[14:17], v[134:137], v[202:205], v[14:17]
	v_mfma_f32_16x16x32_bf16 v[10:13], v[142:145], v[202:205], v[10:13]
	v_mfma_f32_16x16x32_bf16 v[54:57], v[146:149], v[162:165], v[54:57]
	v_mfma_f32_16x16x32_bf16 v[50:53], v[154:157], v[162:165], v[50:53]
	v_mfma_f32_16x16x32_bf16 v[38:41], v[146:149], v[170:173], v[38:41]
	v_mfma_f32_16x16x32_bf16 v[34:37], v[154:157], v[170:173], v[34:37]
	v_mfma_f32_16x16x32_bf16 v[22:25], v[146:149], v[178:181], v[22:25]
	v_mfma_f32_16x16x32_bf16 v[18:21], v[154:157], v[178:181], v[18:21]
	v_mfma_f32_16x16x32_bf16 v[6:9], v[146:149], v[198:201], v[6:9]
	v_mfma_f32_16x16x32_bf16 v[2:5], v[154:157], v[198:201], v[2:5]
	v_mfma_f32_16x16x32_bf16 v[54:57], v[150:153], v[166:169], v[54:57]
	v_mfma_f32_16x16x32_bf16 v[50:53], v[158:161], v[166:169], v[50:53]
	v_mfma_f32_16x16x32_bf16 v[38:41], v[150:153], v[174:177], v[38:41]
	v_mfma_f32_16x16x32_bf16 v[34:37], v[158:161], v[174:177], v[34:37]
	v_mfma_f32_16x16x32_bf16 v[22:25], v[150:153], v[182:185], v[22:25]
	v_mfma_f32_16x16x32_bf16 v[18:21], v[158:161], v[182:185], v[18:21]
	v_mfma_f32_16x16x32_bf16 v[6:9], v[150:153], v[202:205], v[6:9]
	v_mfma_f32_16x16x32_bf16 v[2:5], v[158:161], v[202:205], v[2:5]
	s_barrier
	s_add_i32 s1, 0, 0x18000
	s_add_i32 s47, 0, 0x1c000
	ds_read_b128 v[130:133], v208
	ds_read_b128 v[134:137], v208 offset:1024
	ds_read_b128 v[138:141], v208 offset:2048
	ds_read_b128 v[142:145], v208 offset:3072
	ds_read_b128 v[146:149], v209
	ds_read_b128 v[150:153], v209 offset:1024
	ds_read_b128 v[154:157], v209 offset:2048
	ds_read_b128 v[158:161], v209 offset:3072
	s_mov_b32 m0, s61
	ds_read_b128 v[162:165], v238 offset:32768
	ds_read_b128 v[166:169], v238 offset:33792
	ds_read_b128 v[170:173], v238 offset:34816
	ds_read_b128 v[174:177], v238 offset:35840
	ds_read_b128 v[178:181], v238 offset:36864
	ds_read_b128 v[182:185], v238 offset:37888
	ds_read_b128 v[198:201], v238 offset:38912
	ds_read_b128 v[202:205], v238 offset:39936
	global_load_lds_dwordx4 v194, s[34:35]
	s_mov_b32 m0, s71
	s_nop 0
	global_load_lds_dwordx4 v196, s[34:35]
	s_waitcnt vmcnt(8)
	s_waitcnt lgkmcnt(0)
	s_barrier
	v_mfma_f32_16x16x32_bf16 v[126:129], v[130:133], v[162:165], v[126:129]
	v_mfma_f32_16x16x32_bf16 v[122:125], v[138:141], v[162:165], v[122:125]
	v_mfma_f32_16x16x32_bf16 v[118:121], v[130:133], v[170:173], v[118:121]
	v_mfma_f32_16x16x32_bf16 v[102:105], v[138:141], v[170:173], v[102:105]
	v_mfma_f32_16x16x32_bf16 v[94:97], v[130:133], v[178:181], v[94:97]
	v_mfma_f32_16x16x32_bf16 v[90:93], v[138:141], v[178:181], v[90:93]
	v_mfma_f32_16x16x32_bf16 v[78:81], v[130:133], v[198:201], v[78:81]
	v_mfma_f32_16x16x32_bf16 v[74:77], v[138:141], v[198:201], v[74:77]
	v_mfma_f32_16x16x32_bf16 v[126:129], v[134:137], v[166:169], v[126:129]
	v_mfma_f32_16x16x32_bf16 v[122:125], v[142:145], v[166:169], v[122:125]
	v_mfma_f32_16x16x32_bf16 v[118:121], v[134:137], v[174:177], v[118:121]
	v_mfma_f32_16x16x32_bf16 v[102:105], v[142:145], v[174:177], v[102:105]
	v_mfma_f32_16x16x32_bf16 v[94:97], v[134:137], v[182:185], v[94:97]
	v_mfma_f32_16x16x32_bf16 v[90:93], v[142:145], v[182:185], v[90:93]
	v_mfma_f32_16x16x32_bf16 v[78:81], v[134:137], v[202:205], v[78:81]
	v_mfma_f32_16x16x32_bf16 v[74:77], v[142:145], v[202:205], v[74:77]
	v_mfma_f32_16x16x32_bf16 v[114:117], v[146:149], v[162:165], v[114:117]
	v_mfma_f32_16x16x32_bf16 v[110:113], v[154:157], v[162:165], v[110:113]
	v_mfma_f32_16x16x32_bf16 v[106:109], v[146:149], v[170:173], v[106:109]
	v_mfma_f32_16x16x32_bf16 v[98:101], v[154:157], v[170:173], v[98:101]
	v_mfma_f32_16x16x32_bf16 v[86:89], v[146:149], v[178:181], v[86:89]
	v_mfma_f32_16x16x32_bf16 v[82:85], v[154:157], v[178:181], v[82:85]
	v_mfma_f32_16x16x32_bf16 v[70:73], v[146:149], v[198:201], v[70:73]
	v_mfma_f32_16x16x32_bf16 v[66:69], v[154:157], v[198:201], v[66:69]
	v_mfma_f32_16x16x32_bf16 v[114:117], v[150:153], v[166:169], v[114:117]
	v_mfma_f32_16x16x32_bf16 v[110:113], v[158:161], v[166:169], v[110:113]
	v_mfma_f32_16x16x32_bf16 v[106:109], v[150:153], v[174:177], v[106:109]
	v_mfma_f32_16x16x32_bf16 v[98:101], v[158:161], v[174:177], v[98:101]
	v_mfma_f32_16x16x32_bf16 v[86:89], v[150:153], v[182:185], v[86:89]
	v_mfma_f32_16x16x32_bf16 v[82:85], v[158:161], v[182:185], v[82:85]
	v_mfma_f32_16x16x32_bf16 v[70:73], v[150:153], v[202:205], v[70:73]
	v_mfma_f32_16x16x32_bf16 v[66:69], v[158:161], v[202:205], v[66:69]
	s_barrier
	s_add_i32 s1, s1, s57
	s_add_u32 s66, s66, 0x80
	s_addc_u32 s67, s67, 0
	s_add_u32 s100, s100, 0x80
	s_addc_u32 s101, s101, 0
	s_add_u32 s34, s34, 0x80
	s_addc_u32 s35, s35, 0
	s_mov_b32 m0, s1
	ds_read_b128 v[162:165], v238 offset:49152
	ds_read_b128 v[166:169], v238 offset:50176
	ds_read_b128 v[170:173], v238 offset:51200
	ds_read_b128 v[174:177], v238 offset:52224
	ds_read_b128 v[178:181], v238 offset:53248
	ds_read_b128 v[182:185], v238 offset:54272
	ds_read_b128 v[198:201], v238 offset:55296
	ds_read_b128 v[202:205], v238 offset:56320
	global_load_lds_dwordx4 v188, s[66:67]
	s_add_i32 m0, s1, 0x2000
	s_add_i32 s1, s47, s57
	global_load_lds_dwordx4 v192, s[66:67]
	s_mov_b32 m0, s1
	s_nop 0
	global_load_lds_dwordx4 v188, s[100:101]
	s_add_i32 m0, s1, 0x2000
	s_nop 0
	global_load_lds_dwordx4 v192, s[100:101]
	s_mov_b32 m0, s64
	s_nop 0
	global_load_lds_dwordx4 v186, s[34:35]
	s_mov_b32 m0, s65
	s_nop 0
	global_load_lds_dwordx4 v190, s[34:35]
	s_waitcnt vmcnt(8)
	s_waitcnt lgkmcnt(0)
	s_barrier
	v_mfma_f32_16x16x32_bf16 v[62:65], v[130:133], v[162:165], v[62:65]
	v_mfma_f32_16x16x32_bf16 v[58:61], v[138:141], v[162:165], v[58:61]
	v_mfma_f32_16x16x32_bf16 v[46:49], v[130:133], v[170:173], v[46:49]
	v_mfma_f32_16x16x32_bf16 v[42:45], v[138:141], v[170:173], v[42:45]
	v_mfma_f32_16x16x32_bf16 v[30:33], v[130:133], v[178:181], v[30:33]
	v_mfma_f32_16x16x32_bf16 v[26:29], v[138:141], v[178:181], v[26:29]
	v_mfma_f32_16x16x32_bf16 v[14:17], v[130:133], v[198:201], v[14:17]
	v_mfma_f32_16x16x32_bf16 v[10:13], v[138:141], v[198:201], v[10:13]
	v_mfma_f32_16x16x32_bf16 v[62:65], v[134:137], v[166:169], v[62:65]
	v_mfma_f32_16x16x32_bf16 v[58:61], v[142:145], v[166:169], v[58:61]
	v_mfma_f32_16x16x32_bf16 v[46:49], v[134:137], v[174:177], v[46:49]
	v_mfma_f32_16x16x32_bf16 v[42:45], v[142:145], v[174:177], v[42:45]
	v_mfma_f32_16x16x32_bf16 v[30:33], v[134:137], v[182:185], v[30:33]
	v_mfma_f32_16x16x32_bf16 v[26:29], v[142:145], v[182:185], v[26:29]
	v_mfma_f32_16x16x32_bf16 v[14:17], v[134:137], v[202:205], v[14:17]
	v_mfma_f32_16x16x32_bf16 v[10:13], v[142:145], v[202:205], v[10:13]
	v_mfma_f32_16x16x32_bf16 v[54:57], v[146:149], v[162:165], v[54:57]
	v_mfma_f32_16x16x32_bf16 v[50:53], v[154:157], v[162:165], v[50:53]
	v_mfma_f32_16x16x32_bf16 v[38:41], v[146:149], v[170:173], v[38:41]
	v_mfma_f32_16x16x32_bf16 v[34:37], v[154:157], v[170:173], v[34:37]
	v_mfma_f32_16x16x32_bf16 v[22:25], v[146:149], v[178:181], v[22:25]
	v_mfma_f32_16x16x32_bf16 v[18:21], v[154:157], v[178:181], v[18:21]
	v_mfma_f32_16x16x32_bf16 v[6:9], v[146:149], v[198:201], v[6:9]
	v_mfma_f32_16x16x32_bf16 v[2:5], v[154:157], v[198:201], v[2:5]
	v_mfma_f32_16x16x32_bf16 v[54:57], v[150:153], v[166:169], v[54:57]
	v_mfma_f32_16x16x32_bf16 v[50:53], v[158:161], v[166:169], v[50:53]
	v_mfma_f32_16x16x32_bf16 v[38:41], v[150:153], v[174:177], v[38:41]
	v_mfma_f32_16x16x32_bf16 v[34:37], v[158:161], v[174:177], v[34:37]
	v_mfma_f32_16x16x32_bf16 v[22:25], v[150:153], v[182:185], v[22:25]
	v_mfma_f32_16x16x32_bf16 v[18:21], v[158:161], v[182:185], v[18:21]
	v_mfma_f32_16x16x32_bf16 v[6:9], v[150:153], v[202:205], v[6:9]
	v_mfma_f32_16x16x32_bf16 v[2:5], v[158:161], v[202:205], v[2:5]
	s_barrier
	s_add_u32 s80, s80, 0x100
	s_addc_u32 s81, s81, 0
	s_add_u32 vcc_lo, vcc_lo, 0x100
	s_addc_u32 vcc_hi, vcc_hi, 0
	s_cmp_ge_u32 s0, s91
	s_mov_b32 s34, s0
	s_cbranch_scc0 .LBB0_169
	v_readlane_b32 s0, v243, 28
	v_readlane_b32 s1, v243, 29
	s_and_b64 vcc, exec, s[0:1]
	s_cbranch_vccz .LBB0_174
	s_barrier
	v_lshl_add_u32 v198, s99, 8, v1
	s_cmp_lt_i32 s70, 1
	s_mov_b64 s[34:35], -1
	s_cbranch_scc0 .LBB0_175
